# hand-written rmsnorm+modulate loops (norm1/norm2): scalar addressing, next-row prefetch, DPP reduction
# speedup vs baseline: 1.0116x; 1.0064x over previous
.LBB0_82:
	s_andn2_b64 vcc, exec, s[4:5]
	s_cbranch_vccnz .LBB0_262
	v_readlane_b32 s0, v254, 48
	s_cmp_lt_i32 s0, 4
	s_mov_b64 s[4:5], -1
	s_cbranch_scc1 .LBB0_152
	v_readlane_b32 s0, v254, 48
	s_cmp_lt_i32 s0, 5
	s_cbranch_scc1 .LBB0_93
	v_readlane_b32 s0, v254, 48
	s_cmp_eq_u32 s0, 5
	s_cbranch_scc0 .LBB0_92
	v_mov_b32_e32 v1, v197
	v_readlane_b32 s0, v253, 6
	v_ashrrev_i32_e32 v3, 6, v1
	s_nop 0
	v_add_u32_e32 v68, s0, v3
	s_mov_b32 s0, 0x9000
	v_cmp_gt_i32_e32 vcc, s0, v68
	s_and_saveexec_b64 s[4:5], vcc
	s_cbranch_execz .LBB0_91
	s_waitcnt vmcnt(0) lgkmcnt(0)
	v_readlane_b32 s6, v254, 41
	v_readlane_b32 s7, v254, 42
	v_readfirstlane_b32 s18, v68
	v_readlane_b32 s23, v254, 53
	v_readlane_b32 s3, v253, 7
	s_load_dwordx2 s[0:1], s[6:7], 0x38
	s_load_dwordx4 s[8:11], s[6:7], 0x118
	v_and_b32_e32 v7, 63, v197
	v_lshlrev_b32_e32 v6, 4, v7
	v_lshlrev_b32_e32 v7, 3, v7
	s_lshl_b32 s40, s23, 12
	s_mul_i32 s41, s23, 0x66000
	s_add_u32 s41, s41, 0x4000
	s_waitcnt lgkmcnt(0)
	s_add_u32 s0, s0, s40
	s_addc_u32 s1, s1, 0
	s_add_u32 s12, s10, 0x198100
	s_addc_u32 s13, s11, 0
	s_add_u32 s14, s10, s41
	s_addc_u32 s15, s11, 0
	s_add_u32 s20, s10, 0x3998100
	s_addc_u32 s21, s11, 0
	s_mov_b32 s50, 1
	s_mul_hi_u32 s40, s18, 0x71c72
	s_mul_i32 s41, s40, 0x2400
	s_sub_u32 s41, s18, s41
	s_lshr_b32 s42, s41, 11
	s_lshl2_add_u32 s42, s40, s42
	s_sub_u32 s43, s41, 0x2000
	s_cmp_lt_u32 s41, 0x2000
	s_cselect_b32 s42, s42, 16
	s_cselect_b32 s43, s41, s43
	s_cselect_b32 s44, 25, 22
	s_cselect_b32 s48, s8, s12
	s_cselect_b32 s49, s9, s13
	s_lshl_b32 s44, s40, s44
	s_lshl_b32 s43, s43, 12
	s_add_u32 s43, s43, s44
	s_add_u32 s24, s48, s43
	s_addc_u32 s25, s49, 0
	s_mul_i32 s42, s42, 0x6000
	s_add_u32 s26, s14, s42
	s_addc_u32 s27, s15, 0
	s_lshl_b32 s43, s18, 11
	s_add_u32 s28, s20, s43
	s_addc_u32 s29, s21, 0
	global_load_dwordx4 v[8:11], v6, s[24:25]
	global_load_dwordx4 v[12:15], v6, s[24:25] offset:1024
	global_load_dwordx4 v[16:19], v6, s[24:25] offset:2048
	global_load_dwordx4 v[20:23], v6, s[24:25] offset:3072
	global_load_dwordx4 v[24:27], v6, s[26:27]
	global_load_dwordx4 v[28:31], v6, s[26:27] offset:1024
	global_load_dwordx4 v[32:35], v6, s[26:27] offset:2048
	global_load_dwordx4 v[36:39], v6, s[26:27] offset:3072
	global_load_dwordx4 v[40:43], v6, s[26:27] offset:-4096
	global_load_dwordx4 v[44:47], v6, s[26:27] offset:-3072
	global_load_dwordx4 v[48:51], v6, s[26:27] offset:-2048
	global_load_dwordx4 v[52:55], v6, s[26:27] offset:-1024
	global_load_dwordx4 v[88:91], v6, s[0:1]
	global_load_dwordx4 v[92:95], v6, s[0:1] offset:1024
	global_load_dwordx4 v[96:99], v6, s[0:1] offset:2048
	global_load_dwordx4 v[100:103], v6, s[0:1] offset:3072
.Lnm1_loop:
	s_add_u32 s23, s18, s3
	s_cmp_lt_u32 s23, 0x9000
	s_cbranch_scc0 .Lnm1_lastA
	s_mul_hi_u32 s40, s23, 0x71c72
	s_mul_i32 s41, s40, 0x2400
	s_sub_u32 s41, s23, s41
	s_lshr_b32 s42, s41, 11
	s_lshl2_add_u32 s42, s40, s42
	s_sub_u32 s43, s41, 0x2000
	s_cmp_lt_u32 s41, 0x2000
	s_cselect_b32 s42, s42, 16
	s_cselect_b32 s43, s41, s43
	s_cselect_b32 s44, 25, 22
	s_cselect_b32 s48, s8, s12
	s_cselect_b32 s49, s9, s13
	s_lshl_b32 s44, s40, s44
	s_lshl_b32 s43, s43, 12
	s_add_u32 s43, s43, s44
	s_add_u32 s30, s48, s43
	s_addc_u32 s31, s49, 0
	s_mul_i32 s42, s42, 0x6000
	s_add_u32 s36, s14, s42
	s_addc_u32 s37, s15, 0
	s_lshl_b32 s43, s23, 11
	s_add_u32 s38, s20, s43
	s_addc_u32 s39, s21, 0
	global_load_dwordx4 v[104:107], v6, s[30:31]
	global_load_dwordx4 v[108:111], v6, s[30:31] offset:1024
	global_load_dwordx4 v[112:115], v6, s[30:31] offset:2048
	global_load_dwordx4 v[116:119], v6, s[30:31] offset:3072
	global_load_dwordx4 v[120:123], v6, s[36:37]
	global_load_dwordx4 v[124:127], v6, s[36:37] offset:1024
	global_load_dwordx4 v[128:131], v6, s[36:37] offset:2048
	global_load_dwordx4 v[132:135], v6, s[36:37] offset:3072
	global_load_dwordx4 v[164:167], v6, s[36:37] offset:-4096
	global_load_dwordx4 v[168:171], v6, s[36:37] offset:-3072
	global_load_dwordx4 v[172:175], v6, s[36:37] offset:-2048
	global_load_dwordx4 v[176:179], v6, s[36:37] offset:-1024
	s_waitcnt vmcnt(16)
	v_pk_mul_f32 v[56:57], v[8:9], v[8:9]
	v_pk_mul_f32 v[58:59], v[10:11], v[10:11]
	v_pk_fma_f32 v[56:57], v[12:13], v[12:13], v[56:57]
	v_pk_fma_f32 v[58:59], v[14:15], v[14:15], v[58:59]
	v_pk_fma_f32 v[56:57], v[16:17], v[16:17], v[56:57]
	v_pk_fma_f32 v[58:59], v[18:19], v[18:19], v[58:59]
	v_pk_fma_f32 v[56:57], v[20:21], v[20:21], v[56:57]
	v_pk_fma_f32 v[58:59], v[22:23], v[22:23], v[58:59]
	v_pk_add_f32 v[56:57], v[56:57], v[58:59]
	v_pk_add_f32 v[24:25], v[24:25], 1.0 op_sel_hi:[1,0]
	v_add_f32_e32 v60, v56, v57
	v_pk_add_f32 v[26:27], v[26:27], 1.0 op_sel_hi:[1,0]
	v_pk_add_f32 v[28:29], v[28:29], 1.0 op_sel_hi:[1,0]
	v_add_f32_dpp v60, v60, v60 quad_perm:[1,0,3,2] row_mask:0xf bank_mask:0xf
	v_pk_add_f32 v[30:31], v[30:31], 1.0 op_sel_hi:[1,0]
	v_pk_add_f32 v[32:33], v[32:33], 1.0 op_sel_hi:[1,0]
	v_add_f32_dpp v60, v60, v60 quad_perm:[2,3,0,1] row_mask:0xf bank_mask:0xf
	v_pk_add_f32 v[34:35], v[34:35], 1.0 op_sel_hi:[1,0]
	v_pk_add_f32 v[36:37], v[36:37], 1.0 op_sel_hi:[1,0]
	v_add_f32_dpp v60, v60, v60 row_half_mirror row_mask:0xf bank_mask:0xf
	v_pk_add_f32 v[38:39], v[38:39], 1.0 op_sel_hi:[1,0]
	s_nop 0
	v_add_f32_dpp v60, v60, v60 row_mirror row_mask:0xf bank_mask:0xf
	s_nop 1
	v_readlane_b32 s60, v60, 0
	v_readlane_b32 s61, v60, 16
	v_readlane_b32 s62, v60, 32
	v_readlane_b32 s63, v60, 48
	v_mov_b32_e32 v60, s60
	s_nop 0
	v_add_f32_e32 v60, s61, v60
	v_add_f32_e32 v60, s62, v60
	v_add_f32_e32 v60, s63, v60
	v_fmamk_f32 v60, v60, 0x3a800000, v233
	v_rsq_f32_e32 v62, v60
	s_cmp_eq_u32 s50, 0
	s_cbranch_scc1 .Lnm1_g1
	s_waitcnt vmcnt(12)
	s_mov_b32 s50, 0
.Lnm1_g1:
	v_pk_mul_f32 v[8:9], v[8:9], v[62:63] op_sel_hi:[1,0]
	v_pk_mul_f32 v[10:11], v[10:11], v[62:63] op_sel_hi:[1,0]
	v_pk_mul_f32 v[12:13], v[12:13], v[62:63] op_sel_hi:[1,0]
	v_pk_mul_f32 v[14:15], v[14:15], v[62:63] op_sel_hi:[1,0]
	v_pk_mul_f32 v[16:17], v[16:17], v[62:63] op_sel_hi:[1,0]
	v_pk_mul_f32 v[18:19], v[18:19], v[62:63] op_sel_hi:[1,0]
	v_pk_mul_f32 v[20:21], v[20:21], v[62:63] op_sel_hi:[1,0]
	v_pk_mul_f32 v[22:23], v[22:23], v[62:63] op_sel_hi:[1,0]
	v_pk_mul_f32 v[8:9], v[88:89], v[8:9]
	v_pk_mul_f32 v[10:11], v[90:91], v[10:11]
	v_pk_mul_f32 v[12:13], v[92:93], v[12:13]
	v_pk_mul_f32 v[14:15], v[94:95], v[14:15]
	v_pk_mul_f32 v[16:17], v[96:97], v[16:17]
	v_pk_mul_f32 v[18:19], v[98:99], v[18:19]
	v_pk_mul_f32 v[20:21], v[100:101], v[20:21]
	v_pk_mul_f32 v[22:23], v[102:103], v[22:23]
	v_pk_fma_f32 v[8:9], v[24:25], v[8:9], v[40:41]
	v_pk_fma_f32 v[10:11], v[26:27], v[10:11], v[42:43]
	v_pk_fma_f32 v[12:13], v[28:29], v[12:13], v[44:45]
	v_pk_fma_f32 v[14:15], v[30:31], v[14:15], v[46:47]
	v_pk_fma_f32 v[16:17], v[32:33], v[16:17], v[48:49]
	v_pk_fma_f32 v[18:19], v[34:35], v[18:19], v[50:51]
	v_pk_fma_f32 v[20:21], v[36:37], v[20:21], v[52:53]
	v_pk_fma_f32 v[22:23], v[38:39], v[22:23], v[54:55]
	v_cvt_pk_f16_f32 v8, v8, v9
	v_cvt_pk_f16_f32 v9, v10, v11
	v_cvt_pk_f16_f32 v10, v12, v13
	v_cvt_pk_f16_f32 v11, v14, v15
	v_cvt_pk_f16_f32 v12, v16, v17
	v_cvt_pk_f16_f32 v13, v18, v19
	v_cvt_pk_f16_f32 v14, v20, v21
	v_cvt_pk_f16_f32 v15, v22, v23
	global_store_dwordx2 v7, v[8:9], s[28:29]
	global_store_dwordx2 v7, v[10:11], s[28:29] offset:512
	global_store_dwordx2 v7, v[12:13], s[28:29] offset:1024
	global_store_dwordx2 v7, v[14:15], s[28:29] offset:1536
	s_add_u32 s18, s23, s3
	s_cmp_lt_u32 s18, 0x9000
	s_cbranch_scc0 .Lnm1_lastB
	s_mul_hi_u32 s40, s18, 0x71c72
	s_mul_i32 s41, s40, 0x2400
	s_sub_u32 s41, s18, s41
	s_lshr_b32 s42, s41, 11
	s_lshl2_add_u32 s42, s40, s42
	s_sub_u32 s43, s41, 0x2000
	s_cmp_lt_u32 s41, 0x2000
	s_cselect_b32 s42, s42, 16
	s_cselect_b32 s43, s41, s43
	s_cselect_b32 s44, 25, 22
	s_cselect_b32 s48, s8, s12
	s_cselect_b32 s49, s9, s13
	s_lshl_b32 s44, s40, s44
	s_lshl_b32 s43, s43, 12
	s_add_u32 s43, s43, s44
	s_add_u32 s24, s48, s43
	s_addc_u32 s25, s49, 0
	s_mul_i32 s42, s42, 0x6000
	s_add_u32 s26, s14, s42
	s_addc_u32 s27, s15, 0
	s_lshl_b32 s43, s18, 11
	s_add_u32 s28, s20, s43
	s_addc_u32 s29, s21, 0
	global_load_dwordx4 v[8:11], v6, s[24:25]
	global_load_dwordx4 v[12:15], v6, s[24:25] offset:1024
	global_load_dwordx4 v[16:19], v6, s[24:25] offset:2048
	global_load_dwordx4 v[20:23], v6, s[24:25] offset:3072
	global_load_dwordx4 v[24:27], v6, s[26:27]
	global_load_dwordx4 v[28:31], v6, s[26:27] offset:1024
	global_load_dwordx4 v[32:35], v6, s[26:27] offset:2048
	global_load_dwordx4 v[36:39], v6, s[26:27] offset:3072
	global_load_dwordx4 v[40:43], v6, s[26:27] offset:-4096
	global_load_dwordx4 v[44:47], v6, s[26:27] offset:-3072
	global_load_dwordx4 v[48:51], v6, s[26:27] offset:-2048
	global_load_dwordx4 v[52:55], v6, s[26:27] offset:-1024
	s_waitcnt vmcnt(16)
	v_pk_mul_f32 v[56:57], v[104:105], v[104:105]
	v_pk_mul_f32 v[58:59], v[106:107], v[106:107]
	v_pk_fma_f32 v[56:57], v[108:109], v[108:109], v[56:57]
	v_pk_fma_f32 v[58:59], v[110:111], v[110:111], v[58:59]
	v_pk_fma_f32 v[56:57], v[112:113], v[112:113], v[56:57]
	v_pk_fma_f32 v[58:59], v[114:115], v[114:115], v[58:59]
	v_pk_fma_f32 v[56:57], v[116:117], v[116:117], v[56:57]
	v_pk_fma_f32 v[58:59], v[118:119], v[118:119], v[58:59]
	v_pk_add_f32 v[56:57], v[56:57], v[58:59]
	v_pk_add_f32 v[120:121], v[120:121], 1.0 op_sel_hi:[1,0]
	v_add_f32_e32 v60, v56, v57
	v_pk_add_f32 v[122:123], v[122:123], 1.0 op_sel_hi:[1,0]
	v_pk_add_f32 v[124:125], v[124:125], 1.0 op_sel_hi:[1,0]
	v_add_f32_dpp v60, v60, v60 quad_perm:[1,0,3,2] row_mask:0xf bank_mask:0xf
	v_pk_add_f32 v[126:127], v[126:127], 1.0 op_sel_hi:[1,0]
	v_pk_add_f32 v[128:129], v[128:129], 1.0 op_sel_hi:[1,0]
	v_add_f32_dpp v60, v60, v60 quad_perm:[2,3,0,1] row_mask:0xf bank_mask:0xf
	v_pk_add_f32 v[130:131], v[130:131], 1.0 op_sel_hi:[1,0]
	v_pk_add_f32 v[132:133], v[132:133], 1.0 op_sel_hi:[1,0]
	v_add_f32_dpp v60, v60, v60 row_half_mirror row_mask:0xf bank_mask:0xf
	v_pk_add_f32 v[134:135], v[134:135], 1.0 op_sel_hi:[1,0]
	s_nop 0
	v_add_f32_dpp v60, v60, v60 row_mirror row_mask:0xf bank_mask:0xf
	s_nop 1
	v_readlane_b32 s60, v60, 0
	v_readlane_b32 s61, v60, 16
	v_readlane_b32 s62, v60, 32
	v_readlane_b32 s63, v60, 48
	v_mov_b32_e32 v60, s60
	s_nop 0
	v_add_f32_e32 v60, s61, v60
	v_add_f32_e32 v60, s62, v60
	v_add_f32_e32 v60, s63, v60
	v_fmamk_f32 v60, v60, 0x3a800000, v233
	v_rsq_f32_e32 v62, v60
	s_nop 0
	v_pk_mul_f32 v[104:105], v[104:105], v[62:63] op_sel_hi:[1,0]
	v_pk_mul_f32 v[106:107], v[106:107], v[62:63] op_sel_hi:[1,0]
	v_pk_mul_f32 v[108:109], v[108:109], v[62:63] op_sel_hi:[1,0]
	v_pk_mul_f32 v[110:111], v[110:111], v[62:63] op_sel_hi:[1,0]
	v_pk_mul_f32 v[112:113], v[112:113], v[62:63] op_sel_hi:[1,0]
	v_pk_mul_f32 v[114:115], v[114:115], v[62:63] op_sel_hi:[1,0]
	v_pk_mul_f32 v[116:117], v[116:117], v[62:63] op_sel_hi:[1,0]
	v_pk_mul_f32 v[118:119], v[118:119], v[62:63] op_sel_hi:[1,0]
	v_pk_mul_f32 v[104:105], v[88:89], v[104:105]
	v_pk_mul_f32 v[106:107], v[90:91], v[106:107]
	v_pk_mul_f32 v[108:109], v[92:93], v[108:109]
	v_pk_mul_f32 v[110:111], v[94:95], v[110:111]
	v_pk_mul_f32 v[112:113], v[96:97], v[112:113]
	v_pk_mul_f32 v[114:115], v[98:99], v[114:115]
	v_pk_mul_f32 v[116:117], v[100:101], v[116:117]
	v_pk_mul_f32 v[118:119], v[102:103], v[118:119]
	v_pk_fma_f32 v[104:105], v[120:121], v[104:105], v[164:165]
	v_pk_fma_f32 v[106:107], v[122:123], v[106:107], v[166:167]
	v_pk_fma_f32 v[108:109], v[124:125], v[108:109], v[168:169]
	v_pk_fma_f32 v[110:111], v[126:127], v[110:111], v[170:171]
	v_pk_fma_f32 v[112:113], v[128:129], v[112:113], v[172:173]
	v_pk_fma_f32 v[114:115], v[130:131], v[114:115], v[174:175]
	v_pk_fma_f32 v[116:117], v[132:133], v[116:117], v[176:177]
	v_pk_fma_f32 v[118:119], v[134:135], v[118:119], v[178:179]
	v_cvt_pk_f16_f32 v104, v104, v105
	v_cvt_pk_f16_f32 v105, v106, v107
	v_cvt_pk_f16_f32 v106, v108, v109
	v_cvt_pk_f16_f32 v107, v110, v111
	v_cvt_pk_f16_f32 v108, v112, v113
	v_cvt_pk_f16_f32 v109, v114, v115
	v_cvt_pk_f16_f32 v110, v116, v117
	v_cvt_pk_f16_f32 v111, v118, v119
	global_store_dwordx2 v7, v[104:105], s[38:39]
	global_store_dwordx2 v7, v[106:107], s[38:39] offset:512
	global_store_dwordx2 v7, v[108:109], s[38:39] offset:1024
	global_store_dwordx2 v7, v[110:111], s[38:39] offset:1536
	s_branch .Lnm1_loop
.Lnm1_lastA:
	s_waitcnt vmcnt(0)
	v_pk_mul_f32 v[56:57], v[8:9], v[8:9]
	v_pk_mul_f32 v[58:59], v[10:11], v[10:11]
	v_pk_fma_f32 v[56:57], v[12:13], v[12:13], v[56:57]
	v_pk_fma_f32 v[58:59], v[14:15], v[14:15], v[58:59]
	v_pk_fma_f32 v[56:57], v[16:17], v[16:17], v[56:57]
	v_pk_fma_f32 v[58:59], v[18:19], v[18:19], v[58:59]
	v_pk_fma_f32 v[56:57], v[20:21], v[20:21], v[56:57]
	v_pk_fma_f32 v[58:59], v[22:23], v[22:23], v[58:59]
	v_pk_add_f32 v[56:57], v[56:57], v[58:59]
	v_pk_add_f32 v[24:25], v[24:25], 1.0 op_sel_hi:[1,0]
	v_add_f32_e32 v60, v56, v57
	v_pk_add_f32 v[26:27], v[26:27], 1.0 op_sel_hi:[1,0]
	v_pk_add_f32 v[28:29], v[28:29], 1.0 op_sel_hi:[1,0]
	v_add_f32_dpp v60, v60, v60 quad_perm:[1,0,3,2] row_mask:0xf bank_mask:0xf
	v_pk_add_f32 v[30:31], v[30:31], 1.0 op_sel_hi:[1,0]
	v_pk_add_f32 v[32:33], v[32:33], 1.0 op_sel_hi:[1,0]
	v_add_f32_dpp v60, v60, v60 quad_perm:[2,3,0,1] row_mask:0xf bank_mask:0xf
	v_pk_add_f32 v[34:35], v[34:35], 1.0 op_sel_hi:[1,0]
	v_pk_add_f32 v[36:37], v[36:37], 1.0 op_sel_hi:[1,0]
	v_add_f32_dpp v60, v60, v60 row_half_mirror row_mask:0xf bank_mask:0xf
	v_pk_add_f32 v[38:39], v[38:39], 1.0 op_sel_hi:[1,0]
	s_nop 0
	v_add_f32_dpp v60, v60, v60 row_mirror row_mask:0xf bank_mask:0xf
	s_nop 1
	v_readlane_b32 s60, v60, 0
	v_readlane_b32 s61, v60, 16
	v_readlane_b32 s62, v60, 32
	v_readlane_b32 s63, v60, 48
	v_mov_b32_e32 v60, s60
	s_nop 0
	v_add_f32_e32 v60, s61, v60
	v_add_f32_e32 v60, s62, v60
	v_add_f32_e32 v60, s63, v60
	v_fmamk_f32 v60, v60, 0x3a800000, v233
	v_rsq_f32_e32 v62, v60
	s_nop 0
	v_pk_mul_f32 v[8:9], v[8:9], v[62:63] op_sel_hi:[1,0]
	v_pk_mul_f32 v[10:11], v[10:11], v[62:63] op_sel_hi:[1,0]
	v_pk_mul_f32 v[12:13], v[12:13], v[62:63] op_sel_hi:[1,0]
	v_pk_mul_f32 v[14:15], v[14:15], v[62:63] op_sel_hi:[1,0]
	v_pk_mul_f32 v[16:17], v[16:17], v[62:63] op_sel_hi:[1,0]
	v_pk_mul_f32 v[18:19], v[18:19], v[62:63] op_sel_hi:[1,0]
	v_pk_mul_f32 v[20:21], v[20:21], v[62:63] op_sel_hi:[1,0]
	v_pk_mul_f32 v[22:23], v[22:23], v[62:63] op_sel_hi:[1,0]
	v_pk_mul_f32 v[8:9], v[88:89], v[8:9]
	v_pk_mul_f32 v[10:11], v[90:91], v[10:11]
	v_pk_mul_f32 v[12:13], v[92:93], v[12:13]
	v_pk_mul_f32 v[14:15], v[94:95], v[14:15]
	v_pk_mul_f32 v[16:17], v[96:97], v[16:17]
	v_pk_mul_f32 v[18:19], v[98:99], v[18:19]
	v_pk_mul_f32 v[20:21], v[100:101], v[20:21]
	v_pk_mul_f32 v[22:23], v[102:103], v[22:23]
	v_pk_fma_f32 v[8:9], v[24:25], v[8:9], v[40:41]
	v_pk_fma_f32 v[10:11], v[26:27], v[10:11], v[42:43]
	v_pk_fma_f32 v[12:13], v[28:29], v[12:13], v[44:45]
	v_pk_fma_f32 v[14:15], v[30:31], v[14:15], v[46:47]
	v_pk_fma_f32 v[16:17], v[32:33], v[16:17], v[48:49]
	v_pk_fma_f32 v[18:19], v[34:35], v[18:19], v[50:51]
	v_pk_fma_f32 v[20:21], v[36:37], v[20:21], v[52:53]
	v_pk_fma_f32 v[22:23], v[38:39], v[22:23], v[54:55]
	v_cvt_pk_f16_f32 v8, v8, v9
	v_cvt_pk_f16_f32 v9, v10, v11
	v_cvt_pk_f16_f32 v10, v12, v13
	v_cvt_pk_f16_f32 v11, v14, v15
	v_cvt_pk_f16_f32 v12, v16, v17
	v_cvt_pk_f16_f32 v13, v18, v19
	v_cvt_pk_f16_f32 v14, v20, v21
	v_cvt_pk_f16_f32 v15, v22, v23
	global_store_dwordx2 v7, v[8:9], s[28:29]
	global_store_dwordx2 v7, v[10:11], s[28:29] offset:512
	global_store_dwordx2 v7, v[12:13], s[28:29] offset:1024
	global_store_dwordx2 v7, v[14:15], s[28:29] offset:1536
	s_branch .Lnm1_done
.Lnm1_lastB:
	s_waitcnt vmcnt(0)
	v_pk_mul_f32 v[56:57], v[104:105], v[104:105]
	v_pk_mul_f32 v[58:59], v[106:107], v[106:107]
	v_pk_fma_f32 v[56:57], v[108:109], v[108:109], v[56:57]
	v_pk_fma_f32 v[58:59], v[110:111], v[110:111], v[58:59]
	v_pk_fma_f32 v[56:57], v[112:113], v[112:113], v[56:57]
	v_pk_fma_f32 v[58:59], v[114:115], v[114:115], v[58:59]
	v_pk_fma_f32 v[56:57], v[116:117], v[116:117], v[56:57]
	v_pk_fma_f32 v[58:59], v[118:119], v[118:119], v[58:59]
	v_pk_add_f32 v[56:57], v[56:57], v[58:59]
	v_pk_add_f32 v[120:121], v[120:121], 1.0 op_sel_hi:[1,0]
	v_add_f32_e32 v60, v56, v57
	v_pk_add_f32 v[122:123], v[122:123], 1.0 op_sel_hi:[1,0]
	v_pk_add_f32 v[124:125], v[124:125], 1.0 op_sel_hi:[1,0]
	v_add_f32_dpp v60, v60, v60 quad_perm:[1,0,3,2] row_mask:0xf bank_mask:0xf
	v_pk_add_f32 v[126:127], v[126:127], 1.0 op_sel_hi:[1,0]
	v_pk_add_f32 v[128:129], v[128:129], 1.0 op_sel_hi:[1,0]
	v_add_f32_dpp v60, v60, v60 quad_perm:[2,3,0,1] row_mask:0xf bank_mask:0xf
	v_pk_add_f32 v[130:131], v[130:131], 1.0 op_sel_hi:[1,0]
	v_pk_add_f32 v[132:133], v[132:133], 1.0 op_sel_hi:[1,0]
	v_add_f32_dpp v60, v60, v60 row_half_mirror row_mask:0xf bank_mask:0xf
	v_pk_add_f32 v[134:135], v[134:135], 1.0 op_sel_hi:[1,0]
	s_nop 0
	v_add_f32_dpp v60, v60, v60 row_mirror row_mask:0xf bank_mask:0xf
	s_nop 1
	v_readlane_b32 s60, v60, 0
	v_readlane_b32 s61, v60, 16
	v_readlane_b32 s62, v60, 32
	v_readlane_b32 s63, v60, 48
	v_mov_b32_e32 v60, s60
	s_nop 0
	v_add_f32_e32 v60, s61, v60
	v_add_f32_e32 v60, s62, v60
	v_add_f32_e32 v60, s63, v60
	v_fmamk_f32 v60, v60, 0x3a800000, v233
	v_rsq_f32_e32 v62, v60
	s_nop 0
	v_pk_mul_f32 v[104:105], v[104:105], v[62:63] op_sel_hi:[1,0]
	v_pk_mul_f32 v[106:107], v[106:107], v[62:63] op_sel_hi:[1,0]
	v_pk_mul_f32 v[108:109], v[108:109], v[62:63] op_sel_hi:[1,0]
	v_pk_mul_f32 v[110:111], v[110:111], v[62:63] op_sel_hi:[1,0]
	v_pk_mul_f32 v[112:113], v[112:113], v[62:63] op_sel_hi:[1,0]
	v_pk_mul_f32 v[114:115], v[114:115], v[62:63] op_sel_hi:[1,0]
	v_pk_mul_f32 v[116:117], v[116:117], v[62:63] op_sel_hi:[1,0]
	v_pk_mul_f32 v[118:119], v[118:119], v[62:63] op_sel_hi:[1,0]
	v_pk_mul_f32 v[104:105], v[88:89], v[104:105]
	v_pk_mul_f32 v[106:107], v[90:91], v[106:107]
	v_pk_mul_f32 v[108:109], v[92:93], v[108:109]
	v_pk_mul_f32 v[110:111], v[94:95], v[110:111]
	v_pk_mul_f32 v[112:113], v[96:97], v[112:113]
	v_pk_mul_f32 v[114:115], v[98:99], v[114:115]
	v_pk_mul_f32 v[116:117], v[100:101], v[116:117]
	v_pk_mul_f32 v[118:119], v[102:103], v[118:119]
	v_pk_fma_f32 v[104:105], v[120:121], v[104:105], v[164:165]
	v_pk_fma_f32 v[106:107], v[122:123], v[106:107], v[166:167]
	v_pk_fma_f32 v[108:109], v[124:125], v[108:109], v[168:169]
	v_pk_fma_f32 v[110:111], v[126:127], v[110:111], v[170:171]
	v_pk_fma_f32 v[112:113], v[128:129], v[112:113], v[172:173]
	v_pk_fma_f32 v[114:115], v[130:131], v[114:115], v[174:175]
	v_pk_fma_f32 v[116:117], v[132:133], v[116:117], v[176:177]
	v_pk_fma_f32 v[118:119], v[134:135], v[118:119], v[178:179]
	v_cvt_pk_f16_f32 v104, v104, v105
	v_cvt_pk_f16_f32 v105, v106, v107
	v_cvt_pk_f16_f32 v106, v108, v109
	v_cvt_pk_f16_f32 v107, v110, v111
	v_cvt_pk_f16_f32 v108, v112, v113
	v_cvt_pk_f16_f32 v109, v114, v115
	v_cvt_pk_f16_f32 v110, v116, v117
	v_cvt_pk_f16_f32 v111, v118, v119
	global_store_dwordx2 v7, v[104:105], s[38:39]
	global_store_dwordx2 v7, v[106:107], s[38:39] offset:512
	global_store_dwordx2 v7, v[108:109], s[38:39] offset:1024
	global_store_dwordx2 v7, v[110:111], s[38:39] offset:1536
.Lnm1_done:
.LBB0_91:
	s_or_b64 exec, exec, s[4:5]
.LBB0_92:
	s_mov_b64 s[4:5], 0

.LBB0_254:
	s_andn2_b64 vcc, exec, s[4:5]
	s_cbranch_vccnz .LBB0_262
	v_readlane_b32 s0, v254, 48
	s_cmp_lg_u32 s0, 1
	s_cbranch_scc1 .LBB0_262
	v_mov_b32_e32 v1, v197
	v_readlane_b32 s0, v253, 6
	v_ashrrev_i32_e32 v3, 6, v1
	s_nop 0
	v_add_u32_e32 v4, s0, v3
	s_mov_b32 s0, 0x9000
	v_cmp_gt_i32_e32 vcc, s0, v4
	s_and_saveexec_b64 s[4:5], vcc
	s_cbranch_execz .LBB0_261
	s_waitcnt vmcnt(0) lgkmcnt(0)
	v_readlane_b32 s6, v254, 41
	v_readlane_b32 s7, v254, 42
	v_readfirstlane_b32 s18, v4
	v_readlane_b32 s23, v254, 53
	v_readlane_b32 s3, v253, 7
	s_load_dwordx2 s[0:1], s[6:7], 0x30
	s_load_dwordx4 s[8:11], s[6:7], 0x118
	v_and_b32_e32 v7, 63, v197
	v_lshlrev_b32_e32 v6, 4, v7
	v_lshlrev_b32_e32 v7, 3, v7
	s_lshl_b32 s40, s23, 12
	s_mul_i32 s41, s23, 0x66000
	s_add_u32 s41, s41, 0x1000
	s_waitcnt lgkmcnt(0)
	s_add_u32 s0, s0, s40
	s_addc_u32 s1, s1, 0
	s_add_u32 s12, s10, 0x198100
	s_addc_u32 s13, s11, 0
	s_add_u32 s14, s10, s41
	s_addc_u32 s15, s11, 0
	s_add_u32 s20, s10, 0x3998100
	s_addc_u32 s21, s11, 0
	s_mov_b32 s50, 1
	s_mul_hi_u32 s40, s18, 0x71c72
	s_mul_i32 s41, s40, 0x2400
	s_sub_u32 s41, s18, s41
	s_lshr_b32 s42, s41, 11
	s_lshl2_add_u32 s42, s40, s42
	s_sub_u32 s43, s41, 0x2000
	s_cmp_lt_u32 s41, 0x2000
	s_cselect_b32 s42, s42, 16
	s_cselect_b32 s43, s41, s43
	s_cselect_b32 s44, 25, 22
	s_cselect_b32 s48, s8, s12
	s_cselect_b32 s49, s9, s13
	s_lshl_b32 s44, s40, s44
	s_lshl_b32 s43, s43, 12
	s_add_u32 s43, s43, s44
	s_add_u32 s24, s48, s43
	s_addc_u32 s25, s49, 0
	s_mul_i32 s42, s42, 0x6000
	s_add_u32 s26, s14, s42
	s_addc_u32 s27, s15, 0
	s_lshl_b32 s43, s18, 11
	s_add_u32 s28, s20, s43
	s_addc_u32 s29, s21, 0
	global_load_dwordx4 v[8:11], v6, s[24:25]
	global_load_dwordx4 v[12:15], v6, s[24:25] offset:1024
	global_load_dwordx4 v[16:19], v6, s[24:25] offset:2048
	global_load_dwordx4 v[20:23], v6, s[24:25] offset:3072
	global_load_dwordx4 v[24:27], v6, s[26:27]
	global_load_dwordx4 v[28:31], v6, s[26:27] offset:1024
	global_load_dwordx4 v[32:35], v6, s[26:27] offset:2048
	global_load_dwordx4 v[36:39], v6, s[26:27] offset:3072
	global_load_dwordx4 v[40:43], v6, s[26:27] offset:-4096
	global_load_dwordx4 v[44:47], v6, s[26:27] offset:-3072
	global_load_dwordx4 v[48:51], v6, s[26:27] offset:-2048
	global_load_dwordx4 v[52:55], v6, s[26:27] offset:-1024
	global_load_dwordx4 v[88:91], v6, s[0:1]
	global_load_dwordx4 v[92:95], v6, s[0:1] offset:1024
	global_load_dwordx4 v[96:99], v6, s[0:1] offset:2048
	global_load_dwordx4 v[100:103], v6, s[0:1] offset:3072

.Lnm0_done:
.LBB0_261:
	s_or_b64 exec, exec, s[4:5]
.LBB0_262:
	s_mov_b64 s[4:5], 0
